# k30: k28 + attention unit epilogue: the 8 gate loads hoisted to the epilogue start into free registers (v96-v127), copied at the original sites
# baseline (speedup 1.0000x reference)
; __device__ __forceinline__ unsigned f2bf(float f) { return pk2(f, f) & 0xffffu; }
; __device__ __forceinline__ int crow(int r, int hi) { return (r & 3) + 8 * (r >> 2) + 4 * hi; }
; __device__ __forceinline__ void attn_body(const bf16_t* Qb, const bf16_t* Kh, const bf16_t* Vh, const bf16_t* Gb, bf16_t* Ob, int seq, char* lds,
;                                           const float* qgain, const float* cosA, const float* sinA, int t0) {
;     ...
;   if (hi == 0) li_l[r32] = l_reg; asm volatile("s_waitcnt lgkmcnt(0)" ::: "memory");
;   float rli[16];
; #pragma unroll
;   for (int r = 0; r < 16; ++r) rli[r] = __builtin_amdgcn_rcpf(li_l[crow(r, hi)]);
;   __syncthreads();
;   char* ot = lds + wid * 8704;
; #pragma unroll
;   for (int r = 0; r < 16; ++r) { const int orow = crow(r, hi);
; #pragma unroll
;     for (int d0 = 0; d0 < 4; ++d0) *(bf16_t*)(ot + orow * 272 + (d0 * 32 + r32) * 2) = (bf16_t)f2bf(o[d0][r] * rli[r]); }
;   asm volatile("s_waitcnt lgkmcnt(0)" ::: "memory");
;   bf16_t* Ow = Ob + (long)(wid * QBLK) * LDO; const bf16_t* Gw = Gb + (long)(wid * QBLK) * LDQ;
;   u32x4 gq[8];
; #pragma unroll
;   for (int k = 0; k < 8; ++k) { const int pc = lane & 15, row = (lane >> 4) + 4 * k; gq[k] = *(const u32x4*)(Gw + (long)row * LDQ + pc * 8); }
.LBB0_257:
	s_or_b64 exec, exec, s[38:39]
	s_or_b32 s20, s15, s17
	s_waitcnt lgkmcnt(0)
	v_add_u32_e32 v72, v187, v176
	s_ashr_i32 s21, s20, 31
	ds_read_b128 v[64:67], v72
	ds_read_b128 v[68:71], v72 offset:32
	s_lshl_b64 s[20:21], s[20:21], 12
	s_add_u32 s15, s8, s20
	s_addc_u32 s17, s9, s21
	s_lshl_b32 s18, s18, 1
	s_add_u32 s16, s16, s18
	s_addc_u32 s14, s14, 0
	s_waitcnt lgkmcnt(1)
	v_rcp_f32_e32 v73, v64
	s_add_u32 s36, s16, 0x1800
	s_addc_u32 s37, s14, 0
	s_movk_i32 s14, 0x2200
	v_rcp_f32_e32 v74, v65
	v_rcp_f32_e32 v75, v66
	v_rcp_f32_e32 v76, v67
	s_waitcnt lgkmcnt(0)
	v_rcp_f32_e32 v77, v68
	ds_read_b128 v[64:67], v72 offset:64
	v_rcp_f32_e32 v78, v69
	v_rcp_f32_e32 v79, v70
	v_rcp_f32_e32 v80, v71
	ds_read_b128 v[68:71], v72 offset:96
	v_mul_lo_u32 v72, v179, s14
	v_add_u32_e32 v72, 0, v72
	v_lshlrev_b32_e32 v81, 1, v181
	v_mul_u32_u24_e32 v82, 0x440, v184
	v_mul_f32_e32 v0, v0, v73
	v_add3_u32 v81, v72, v81, v82
	v_cvt_pk_bf16_f32 v0, v0, v0
	s_waitcnt lgkmcnt(0)
	s_barrier
	v_mov_b64_e32 v[128:129], s[36:37]
	v_lshrrev_b32_e32 v134, 4, v186
	v_mad_i64_i32 v[128:129], vcc, v178, s72, v[128:129]
	v_lshlrev_b32_e32 v132, 1, v180
	v_mov_b32_e32 v133, 0
	v_mul_u32_u24_e32 v134, 0x1400, v134
	v_lshl_add_u64 v[128:129], v[128:129], 0, v[132:133]
	v_lshlrev_b32_e32 v132, 1, v134
	v_lshl_add_u64 v[130:131], v[128:129], 0, v[132:133]
	global_load_dwordx4 v[96:99], v[130:131], off
	v_add_co_u32_e32 v130, vcc, 0xa000, v130
	s_nop 1
	v_addc_co_u32_e32 v131, vcc, 0, v131, vcc
	global_load_dwordx4 v[100:103], v[130:131], off
	v_add_co_u32_e32 v130, vcc, 0xa000, v130
	s_nop 1
	v_addc_co_u32_e32 v131, vcc, 0, v131, vcc
	global_load_dwordx4 v[104:107], v[130:131], off
	v_add_co_u32_e32 v130, vcc, 0xa000, v130
	s_nop 1
	v_addc_co_u32_e32 v131, vcc, 0, v131, vcc
	global_load_dwordx4 v[108:111], v[130:131], off
	v_add_co_u32_e32 v130, vcc, 0xa000, v130
	s_nop 1
	v_addc_co_u32_e32 v131, vcc, 0, v131, vcc
	global_load_dwordx4 v[112:115], v[130:131], off
	v_add_co_u32_e32 v130, vcc, 0xa000, v130
	s_nop 1
	v_addc_co_u32_e32 v131, vcc, 0, v131, vcc
	global_load_dwordx4 v[116:119], v[130:131], off
	v_add_co_u32_e32 v130, vcc, 0xa000, v130
	s_nop 1
	v_addc_co_u32_e32 v131, vcc, 0, v131, vcc
	global_load_dwordx4 v[120:123], v[130:131], off
	v_add_co_u32_e32 v130, vcc, 0xa000, v130
	s_nop 1
	v_addc_co_u32_e32 v131, vcc, 0, v131, vcc
	global_load_dwordx4 v[124:127], v[130:131], off
	ds_write_b16 v81, v0
	v_mul_f32_e32 v0, v48, v73
	v_cvt_pk_bf16_f32 v0, v0, v0
	ds_write_b16 v81, v0 offset:64
	v_mul_f32_e32 v0, v32, v73
	v_cvt_pk_bf16_f32 v0, v0, v0
	ds_write_b16 v81, v0 offset:128
	v_mul_f32_e32 v0, v16, v73
	v_cvt_pk_bf16_f32 v0, v0, v0
	ds_write_b16 v81, v0 offset:192
	v_mul_f32_e32 v0, v1, v74
	v_cvt_pk_bf16_f32 v0, v0, v0
	ds_write_b16 v81, v0 offset:272
	v_mul_f32_e32 v0, v49, v74
	v_cvt_pk_bf16_f32 v0, v0, v0
	ds_write_b16 v81, v0 offset:336
	v_mul_f32_e32 v0, v33, v74
	v_cvt_pk_bf16_f32 v0, v0, v0
	ds_write_b16 v81, v0 offset:400
	v_mul_f32_e32 v0, v17, v74
	v_cvt_pk_bf16_f32 v0, v0, v0
	ds_write_b16 v81, v0 offset:464
	v_mul_f32_e32 v0, v2, v75
	v_cvt_pk_bf16_f32 v0, v0, v0
	ds_write_b16 v81, v0 offset:544
	v_mul_f32_e32 v0, v50, v75
	v_cvt_pk_bf16_f32 v0, v0, v0
	ds_write_b16 v81, v0 offset:608
	v_mul_f32_e32 v0, v34, v75
	v_cvt_pk_bf16_f32 v0, v0, v0
	ds_write_b16 v81, v0 offset:672
	v_mul_f32_e32 v0, v18, v75
	v_cvt_pk_bf16_f32 v0, v0, v0
	ds_write_b16 v81, v0 offset:736
	v_mul_f32_e32 v0, v3, v76
	v_cvt_pk_bf16_f32 v0, v0, v0
	ds_write_b16 v81, v0 offset:816
	v_mul_f32_e32 v0, v51, v76
	v_cvt_pk_bf16_f32 v0, v0, v0
	ds_write_b16 v81, v0 offset:880
	v_mul_f32_e32 v0, v35, v76
	v_cvt_pk_bf16_f32 v0, v0, v0
	ds_write_b16 v81, v0 offset:944
	v_mul_f32_e32 v0, v19, v76
	v_cvt_pk_bf16_f32 v0, v0, v0
	ds_write_b16 v81, v0 offset:1008
	v_mul_f32_e32 v0, v4, v77
	v_cvt_pk_bf16_f32 v0, v0, v0
	ds_write_b16 v81, v0 offset:2176
	v_mul_f32_e32 v0, v52, v77
	v_cvt_pk_bf16_f32 v0, v0, v0
	ds_write_b16 v81, v0 offset:2240
	v_mul_f32_e32 v0, v36, v77
	v_cvt_pk_bf16_f32 v0, v0, v0
	ds_write_b16 v81, v0 offset:2304
	v_mul_f32_e32 v0, v20, v77
	v_cvt_pk_bf16_f32 v0, v0, v0
	ds_write_b16 v81, v0 offset:2368
	v_mul_f32_e32 v0, v5, v78
	v_cvt_pk_bf16_f32 v0, v0, v0
	ds_write_b16 v81, v0 offset:2448
	v_mul_f32_e32 v0, v53, v78
	v_cvt_pk_bf16_f32 v0, v0, v0
	ds_write_b16 v81, v0 offset:2512
	v_mul_f32_e32 v0, v37, v78
	v_cvt_pk_bf16_f32 v0, v0, v0
	ds_write_b16 v81, v0 offset:2576
	v_mul_f32_e32 v0, v21, v78
	v_cvt_pk_bf16_f32 v0, v0, v0
	ds_write_b16 v81, v0 offset:2640
	v_mul_f32_e32 v0, v6, v79
	v_cvt_pk_bf16_f32 v0, v0, v0
	ds_write_b16 v81, v0 offset:2720
	v_mul_f32_e32 v0, v54, v79
	v_cvt_pk_bf16_f32 v0, v0, v0
	ds_write_b16 v81, v0 offset:2784
	v_mul_f32_e32 v0, v38, v79
	v_cvt_pk_bf16_f32 v0, v0, v0
	ds_write_b16 v81, v0 offset:2848
	v_mul_f32_e32 v0, v22, v79
	v_cvt_pk_bf16_f32 v0, v0, v0
	ds_write_b16 v81, v0 offset:2912
	v_mul_f32_e32 v0, v7, v80
	v_cvt_pk_bf16_f32 v0, v0, v0
	ds_write_b16 v81, v0 offset:2992
	v_mul_f32_e32 v0, v55, v80
	v_cvt_pk_bf16_f32 v0, v0, v0
	v_rcp_f32_e32 v64, v64
	ds_write_b16 v81, v0 offset:3056
	v_mul_f32_e32 v0, v39, v80
	v_cvt_pk_bf16_f32 v0, v0, v0
	ds_write_b16 v81, v0 offset:3120
	v_mul_f32_e32 v0, v23, v80
	v_cvt_pk_bf16_f32 v0, v0, v0
	ds_write_b16 v81, v0 offset:3184
	v_mul_f32_e32 v0, v8, v64
	v_cvt_pk_bf16_f32 v0, v0, v0
	ds_write_b16 v81, v0 offset:4352
	v_mul_f32_e32 v0, v56, v64
	v_cvt_pk_bf16_f32 v0, v0, v0
	v_rcp_f32_e32 v65, v65
	ds_write_b16 v81, v0 offset:4416
	v_mul_f32_e32 v0, v40, v64
	v_cvt_pk_bf16_f32 v0, v0, v0
	ds_write_b16 v81, v0 offset:4480
	v_mul_f32_e32 v0, v24, v64
	v_cvt_pk_bf16_f32 v0, v0, v0
; __device__ __forceinline__ unsigned f2bf(float f) { return pk2(f, f) & 0xffffu; }
; __device__ __forceinline__ float silu_f(float g) { return g * __builtin_amdgcn_rcpf(1.f + __expf(-g)); }
; __device__ __forceinline__ int crow(int r, int hi) { return (r & 3) + 8 * (r >> 2) + 4 * hi; }
; __device__ __forceinline__ unsigned cvtpk(float lo, float hi) { unsigned r; asm volatile("v_cvt_pk_bf16_f32 %0, %1, %2" : "=v"(r) : "v"(lo), "v"(hi)); return r; }
; __device__ __forceinline__ unsigned cvtpk(float lo, float hi) { unsigned r; asm volatile("v_cvt_pk_bf16_f32 %0, %1, %2" : "=v"(r) : "v"(lo), "v"(hi)); return r; }
; __device__ __forceinline__ void attn_body(const bf16_t* Qb, const bf16_t* Kh, const bf16_t* Vh, const bf16_t* Gb, bf16_t* Ob, int seq, char* lds,
;                                           const float* qgain, const float* cosA, const float* sinA, int t0) {
;     ...
;   for (int r = 0; r < 16; ++r) { const int orow = crow(r, hi);
; #pragma unroll
;     for (int d0 = 0; d0 < 4; ++d0) *(bf16_t*)(ot + orow * 272 + (d0 * 32 + r32) * 2) = (bf16_t)f2bf(o[d0][r] * rli[r]); }
;   asm volatile("s_waitcnt lgkmcnt(0)" ::: "memory");
;   bf16_t* Ow = Ob + (long)(wid * QBLK) * LDO; const bf16_t* Gw = Gb + (long)(wid * QBLK) * LDQ;
;   u32x4 gq[8];
; #pragma unroll
;   for (int k = 0; k < 8; ++k) { const int pc = lane & 15, row = (lane >> 4) + 4 * k; gq[k] = *(const u32x4*)(Gw + (long)row * LDQ + pc * 8); }
; #pragma unroll
;   for (int k = 0; k < 8; ++k) { const int pc = lane & 15, row = (lane >> 4) + 4 * k; const u32x4 ov = *(const u32x4*)(ot + row * 272 + pc * 16); u32x4 w;
; #pragma unroll
;     for (int e = 0; e < 4; ++e) w[e] = cvtpk(bflo(ov[e]) * silu_f(bflo(gq[k][e])), bfhi(ov[e]) * silu_f(bfhi(gq[k][e])));
	ds_write_b16 v81, v0 offset:4544
	v_mul_f32_e32 v0, v9, v65
	v_cvt_pk_bf16_f32 v0, v0, v0
	ds_write_b16 v81, v0 offset:4624
	v_mul_f32_e32 v0, v57, v65
	v_cvt_pk_bf16_f32 v0, v0, v0
	v_rcp_f32_e32 v66, v66
	ds_write_b16 v81, v0 offset:4688
	v_mul_f32_e32 v0, v41, v65
	v_cvt_pk_bf16_f32 v0, v0, v0
	ds_write_b16 v81, v0 offset:4752
	v_mul_f32_e32 v0, v25, v65
	v_cvt_pk_bf16_f32 v0, v0, v0
	ds_write_b16 v81, v0 offset:4816
	v_mul_f32_e32 v0, v10, v66
	v_cvt_pk_bf16_f32 v0, v0, v0
	ds_write_b16 v81, v0 offset:4896
	v_mul_f32_e32 v0, v58, v66
	v_cvt_pk_bf16_f32 v0, v0, v0
	v_rcp_f32_e32 v67, v67
	ds_write_b16 v81, v0 offset:4960
	v_mul_f32_e32 v0, v42, v66
	v_cvt_pk_bf16_f32 v0, v0, v0
	ds_write_b16 v81, v0 offset:5024
	v_mul_f32_e32 v0, v26, v66
	v_cvt_pk_bf16_f32 v0, v0, v0
	ds_write_b16 v81, v0 offset:5088
	v_mul_f32_e32 v0, v11, v67
	v_cvt_pk_bf16_f32 v0, v0, v0
	ds_write_b16 v81, v0 offset:5168
	v_mul_f32_e32 v0, v59, v67
	v_cvt_pk_bf16_f32 v0, v0, v0
	v_rcp_f32_e32 v68, v68
	ds_write_b16 v81, v0 offset:5232
	v_mul_f32_e32 v0, v43, v67
	v_cvt_pk_bf16_f32 v0, v0, v0
	ds_write_b16 v81, v0 offset:5296
	v_mul_f32_e32 v0, v27, v67
	v_cvt_pk_bf16_f32 v0, v0, v0
	ds_write_b16 v81, v0 offset:5360
	v_mul_f32_e32 v0, v12, v68
	v_cvt_pk_bf16_f32 v0, v0, v0
	ds_write_b16 v81, v0 offset:6528
	v_mul_f32_e32 v0, v60, v68
	v_cvt_pk_bf16_f32 v0, v0, v0
	v_rcp_f32_e32 v69, v69
	ds_write_b16 v81, v0 offset:6592
	v_mul_f32_e32 v0, v44, v68
	v_cvt_pk_bf16_f32 v0, v0, v0
	ds_write_b16 v81, v0 offset:6656
	v_mul_f32_e32 v0, v28, v68
	v_cvt_pk_bf16_f32 v0, v0, v0
	ds_write_b16 v81, v0 offset:6720
	v_mul_f32_e32 v0, v13, v69
	v_cvt_pk_bf16_f32 v0, v0, v0
	ds_write_b16 v81, v0 offset:6800
	v_mul_f32_e32 v0, v61, v69
	v_cvt_pk_bf16_f32 v0, v0, v0
	v_rcp_f32_e32 v70, v70
	ds_write_b16 v81, v0 offset:6864
	v_mul_f32_e32 v0, v45, v69
	v_cvt_pk_bf16_f32 v0, v0, v0
	ds_write_b16 v81, v0 offset:6928
	v_mul_f32_e32 v0, v29, v69
	v_cvt_pk_bf16_f32 v0, v0, v0
	ds_write_b16 v81, v0 offset:6992
	v_mul_f32_e32 v0, v14, v70
	v_cvt_pk_bf16_f32 v0, v0, v0
	ds_write_b16 v81, v0 offset:7072
	v_mul_f32_e32 v0, v62, v70
	v_cvt_pk_bf16_f32 v0, v0, v0
	v_rcp_f32_e32 v71, v71
	ds_write_b16 v81, v0 offset:7136
	v_mul_f32_e32 v0, v46, v70
	v_cvt_pk_bf16_f32 v0, v0, v0
	ds_write_b16 v81, v0 offset:7200
	v_mul_f32_e32 v0, v30, v70
	v_cvt_pk_bf16_f32 v0, v0, v0
	ds_write_b16 v81, v0 offset:7264
	v_mul_f32_e32 v0, v15, v71
	v_cvt_pk_bf16_f32 v0, v0, v0
	ds_write_b16 v81, v0 offset:7344
	v_mul_f32_e32 v0, v63, v71
	v_cvt_pk_bf16_f32 v0, v0, v0
	ds_write_b16 v81, v0 offset:7408
	v_mul_f32_e32 v0, v47, v71
	v_cvt_pk_bf16_f32 v0, v0, v0
	ds_write_b16 v81, v0 offset:7472
	v_mul_f32_e32 v0, v31, v71
	v_cvt_pk_bf16_f32 v0, v0, v0
	ds_write_b16 v81, v0 offset:7536
	v_mov_b64_e32 v[0:1], s[36:37]
	v_lshrrev_b32_e32 v25, 4, v186
	v_mad_i64_i32 v[0:1], s[20:21], v178, s72, v[0:1]
	v_lshlrev_b32_e32 v176, 1, v180
	v_mul_u32_u24_e32 v2, 0x1400, v25
	v_lshl_add_u64 v[0:1], v[0:1], 0, v[176:177]
	v_lshlrev_b32_e32 v176, 1, v2
	s_waitcnt lgkmcnt(0)
	v_lshl_add_u64 v[2:3], v[0:1], 0, v[176:177]
	s_waitcnt vmcnt(0)
	v_mov_b64_e32 v[30:31], v[96:97]
	v_mov_b64_e32 v[32:33], v[98:99]
	s_mov_b32 s16, 0xa000
	v_add_co_u32_e32 v4, vcc, s16, v2
	s_mov_b32 s16, 0x14000
	s_nop 0
	v_addc_co_u32_e32 v5, vcc, 0, v3, vcc
	v_mov_b64_e32 v[34:35], v[100:101]
	v_mov_b64_e32 v[36:37], v[102:103]
	v_add_co_u32_e32 v4, vcc, s16, v2
	s_mov_b32 s16, 0x1e000
	s_nop 0
	v_addc_co_u32_e32 v5, vcc, 0, v3, vcc
	v_add_co_u32_e32 v2, vcc, s16, v2
	v_mov_b64_e32 v[20:21], v[104:105]
	v_mov_b64_e32 v[22:23], v[106:107]
	s_nop 0
	v_addc_co_u32_e32 v3, vcc, 0, v3, vcc
	v_mov_b64_e32 v[16:17], v[108:109]
	v_mov_b64_e32 v[18:19], v[110:111]
	v_add_u32_e32 v2, 0x28000, v176
	v_mov_b32_e32 v3, v177
	v_lshl_add_u64 v[2:3], v[0:1], 0, v[2:3]
	v_add_u32_e32 v4, 0x32000, v176
	v_mov_b32_e32 v5, v177
	v_lshl_add_u64 v[4:5], v[0:1], 0, v[4:5]
	v_mov_b64_e32 v[12:13], v[112:113]
	v_mov_b64_e32 v[14:15], v[114:115]
	v_mov_b64_e32 v[8:9], v[116:117]
	v_mov_b64_e32 v[10:11], v[118:119]
	v_add_u32_e32 v2, 0x3c000, v176
	v_mov_b32_e32 v3, v177
	v_add_u32_e32 v176, 0x46000, v176
	v_lshl_add_u64 v[2:3], v[0:1], 0, v[2:3]
	v_lshlrev_b32_e32 v24, 12, v25
	v_lshl_add_u64 v[0:1], v[0:1], 0, v[176:177]
	v_and_b32_e32 v176, 0xf0, v185
	v_mul_u32_u24_e32 v25, 0x110, v25
	v_add3_u32 v28, v72, v176, v25
	v_mov_b64_e32 v[4:5], v[120:121]
	v_mov_b64_e32 v[6:7], v[122:123]
	s_nop 0
	v_mov_b64_e32 v[0:1], v[124:125]
	v_mov_b64_e32 v[2:3], v[126:127]
	ds_read_b128 v[38:41], v28
	s_add_u32 s14, s15, s18
	v_ashrrev_i32_e32 v179, 31, v178
	s_addc_u32 s15, s17, 0
	v_lshlrev_b64 v[26:27], 12, v[178:179]
	s_waitcnt lgkmcnt(0)
	v_lshlrev_b32_e32 v43, 16, v38
	v_lshl_add_u64 v[26:27], s[14:15], 0, v[26:27]
	v_lshl_add_u64 v[26:27], v[26:27], 0, v[176:177]
	v_or_b32_e32 v176, 0x4000, v24
	v_readlane_b32 s14, v254, 41
	s_add_i32 s48, s48, s54
	s_add_i32 s47, s47, s49
	s_add_i32 s46, s46, s14
	s_cmpk_gt_i32 s48, 0x3ff
	s_waitcnt vmcnt(7)
; __device__ __forceinline__ float silu_f(float g) { return g * __builtin_amdgcn_rcpf(1.f + __expf(-g)); }
; __device__ __forceinline__ unsigned cvtpk(float lo, float hi) { unsigned r; asm volatile("v_cvt_pk_bf16_f32 %0, %1, %2" : "=v"(r) : "v"(lo), "v"(hi)); return r; }
; __device__ __forceinline__ unsigned cvtpk(float lo, float hi) { unsigned r; asm volatile("v_cvt_pk_bf16_f32 %0, %1, %2" : "=v"(r) : "v"(lo), "v"(hi)); return r; }
; __device__ __forceinline__ void attn_body(const bf16_t* Qb, const bf16_t* Kh, const bf16_t* Vh, const bf16_t* Gb, bf16_t* Ob, int seq, char* lds,
;                                           const float* qgain, const float* cosA, const float* sinA, int t0) {
;     ...
;   for (int k = 0; k < 8; ++k) { const int pc = lane & 15, row = (lane >> 4) + 4 * k; const u32x4 ov = *(const u32x4*)(ot + row * 272 + pc * 16); u32x4 w;
; #pragma unroll
;     for (int e = 0; e < 4; ++e) w[e] = cvtpk(bflo(ov[e]) * silu_f(bflo(gq[k][e])), bfhi(ov[e]) * silu_f(bfhi(gq[k][e])));
;     *(u32x4*)(Ow + (long)row * LDO + pc * 8) = w; }
	v_lshlrev_b32_e32 v25, 16, v30
	v_mul_f32_e32 v29, 0xbfb8aa3b, v25
	v_and_b32_e32 v30, 0xffff0000, v30
	v_exp_f32_e32 v29, v29
	v_mul_f32_e32 v42, 0xbfb8aa3b, v30
	v_exp_f32_e32 v42, v42
	v_add_f32_e32 v29, 1.0, v29
	v_rcp_f32_e32 v29, v29
	v_add_f32_e32 v42, 1.0, v42
	v_rcp_f32_e32 v42, v42
	v_mul_f32_e32 v25, v29, v25
	v_mul_f32_e32 v25, v25, v43
	v_and_b32_e32 v29, 0xffff0000, v38
	v_mul_f32_e32 v30, v42, v30
	v_mul_f32_e32 v29, v30, v29
	v_cvt_pk_bf16_f32 v30, v25, v29
	v_lshlrev_b32_e32 v25, 16, v31
	v_mul_f32_e32 v29, 0xbfb8aa3b, v25
	v_and_b32_e32 v31, 0xffff0000, v31
	v_exp_f32_e32 v29, v29
	v_mul_f32_e32 v38, 0xbfb8aa3b, v31
	v_exp_f32_e32 v38, v38
	v_lshlrev_b32_e32 v42, 16, v39
	v_add_f32_e32 v29, 1.0, v29
	v_rcp_f32_e32 v29, v29
	v_add_f32_e32 v38, 1.0, v38
	v_rcp_f32_e32 v38, v38
	v_mul_f32_e32 v25, v29, v25
	v_mul_f32_e32 v25, v25, v42
	v_and_b32_e32 v29, 0xffff0000, v39
	v_mul_f32_e32 v31, v38, v31
	v_mul_f32_e32 v29, v31, v29
	v_cvt_pk_bf16_f32 v31, v25, v29
	v_lshlrev_b32_e32 v25, 16, v32
	v_mul_f32_e32 v29, 0xbfb8aa3b, v25
	v_and_b32_e32 v32, 0xffff0000, v32
	v_exp_f32_e32 v29, v29
	v_mul_f32_e32 v38, 0xbfb8aa3b, v32
	v_exp_f32_e32 v38, v38
	v_lshlrev_b32_e32 v39, 16, v40
	v_add_f32_e32 v29, 1.0, v29
	v_rcp_f32_e32 v29, v29
	v_add_f32_e32 v38, 1.0, v38
	v_rcp_f32_e32 v38, v38
	v_mul_f32_e32 v25, v29, v25
	v_mul_f32_e32 v25, v25, v39
	v_and_b32_e32 v29, 0xffff0000, v40
	v_mul_f32_e32 v32, v38, v32
	v_mul_f32_e32 v29, v32, v29
	v_cvt_pk_bf16_f32 v32, v25, v29
	v_lshlrev_b32_e32 v25, 16, v33
	v_mul_f32_e32 v29, 0xbfb8aa3b, v25
	v_and_b32_e32 v33, 0xffff0000, v33
	v_exp_f32_e32 v29, v29
	v_mul_f32_e32 v38, 0xbfb8aa3b, v33
	v_exp_f32_e32 v38, v38
	v_lshlrev_b32_e32 v39, 16, v41
	v_add_f32_e32 v29, 1.0, v29
	v_rcp_f32_e32 v29, v29
	v_add_f32_e32 v38, 1.0, v38
	v_rcp_f32_e32 v38, v38
	v_mul_f32_e32 v25, v29, v25
	v_mul_f32_e32 v25, v25, v39
	v_and_b32_e32 v29, 0xffff0000, v41
	v_mul_f32_e32 v33, v38, v33
	v_mul_f32_e32 v29, v33, v29
	v_cvt_pk_bf16_f32 v33, v25, v29
	v_mov_b32_e32 v25, v177
	v_lshl_add_u64 v[38:39], v[26:27], 0, v[24:25]
	s_waitcnt vmcnt(6)
	v_lshlrev_b32_e32 v25, 16, v34
	v_mul_f32_e32 v29, 0xbfb8aa3b, v25
	v_and_b32_e32 v34, 0xffff0000, v34
	global_store_dwordx4 v[38:39], v[30:33], off
	v_exp_f32_e32 v29, v29
	v_mul_f32_e32 v38, 0xbfb8aa3b, v34
	v_exp_f32_e32 v38, v38
	ds_read_b128 v[30:33], v28 offset:1088
	v_add_f32_e32 v29, 1.0, v29
	v_rcp_f32_e32 v29, v29
	v_add_f32_e32 v38, 1.0, v38
	v_rcp_f32_e32 v38, v38
	s_waitcnt lgkmcnt(0)
	v_lshlrev_b32_e32 v39, 16, v30
	v_mul_f32_e32 v25, v29, v25
	v_mul_f32_e32 v25, v25, v39
	v_and_b32_e32 v29, 0xffff0000, v30
	v_mul_f32_e32 v30, v38, v34
	v_mul_f32_e32 v29, v30, v29
	v_cvt_pk_bf16_f32 v30, v25, v29
	v_lshlrev_b32_e32 v25, 16, v35
	v_mul_f32_e32 v29, 0xbfb8aa3b, v25
	v_and_b32_e32 v34, 0xffff0000, v35
	v_exp_f32_e32 v29, v29
	v_mul_f32_e32 v35, 0xbfb8aa3b, v34
	v_exp_f32_e32 v35, v35
	v_lshlrev_b32_e32 v38, 16, v31
	v_add_f32_e32 v29, 1.0, v29
	v_rcp_f32_e32 v29, v29
	v_add_f32_e32 v35, 1.0, v35
	v_rcp_f32_e32 v35, v35
	v_mul_f32_e32 v25, v29, v25
	v_mul_f32_e32 v25, v25, v38
	v_and_b32_e32 v29, 0xffff0000, v31
	v_mul_f32_e32 v31, v35, v34
	v_mul_f32_e32 v29, v31, v29
	v_cvt_pk_bf16_f32 v31, v25, v29
	v_lshlrev_b32_e32 v25, 16, v36
	v_mul_f32_e32 v29, 0xbfb8aa3b, v25
	v_and_b32_e32 v34, 0xffff0000, v36
	v_exp_f32_e32 v29, v29
	v_mul_f32_e32 v35, 0xbfb8aa3b, v34
	v_exp_f32_e32 v35, v35
	v_lshlrev_b32_e32 v36, 16, v32
	v_add_f32_e32 v29, 1.0, v29
	v_rcp_f32_e32 v29, v29
	v_add_f32_e32 v35, 1.0, v35
	v_rcp_f32_e32 v35, v35
	v_mul_f32_e32 v25, v29, v25
	v_mul_f32_e32 v25, v25, v36
	v_and_b32_e32 v29, 0xffff0000, v32
	v_mul_f32_e32 v32, v35, v34
	v_mul_f32_e32 v29, v32, v29
	v_cvt_pk_bf16_f32 v32, v25, v29
	v_lshlrev_b32_e32 v25, 16, v37
	v_mul_f32_e32 v29, 0xbfb8aa3b, v25
	v_and_b32_e32 v34, 0xffff0000, v37
	v_exp_f32_e32 v29, v29
	v_mul_f32_e32 v35, 0xbfb8aa3b, v34
	v_exp_f32_e32 v35, v35
	v_lshlrev_b32_e32 v36, 16, v33
	v_add_f32_e32 v29, 1.0, v29
	v_rcp_f32_e32 v29, v29
	v_add_f32_e32 v35, 1.0, v35
	v_rcp_f32_e32 v35, v35
	v_mul_f32_e32 v25, v29, v25
	v_mul_f32_e32 v25, v25, v36
	v_and_b32_e32 v29, 0xffff0000, v33
	v_mul_f32_e32 v33, v35, v34
	v_mul_f32_e32 v29, v33, v29
	v_cvt_pk_bf16_f32 v33, v25, v29
	v_lshl_add_u64 v[34:35], v[26:27], 0, v[176:177]
	s_waitcnt vmcnt(6)
	v_lshlrev_b32_e32 v25, 16, v20
	v_and_b32_e32 v20, 0xffff0000, v20
	global_store_dwordx4 v[34:35], v[30:33], off
	v_mul_f32_e32 v29, 0xbfb8aa3b, v25
	v_mul_f32_e32 v34, 0xbfb8aa3b, v20
	v_exp_f32_e32 v29, v29
	v_exp_f32_e32 v34, v34
	ds_read_b128 v[30:33], v28 offset:2176
	v_or_b32_e32 v176, 0x8000, v24
	v_add_f32_e32 v29, 1.0, v29
	v_add_f32_e32 v34, 1.0, v34
	v_rcp_f32_e32 v29, v29
	v_rcp_f32_e32 v34, v34
	s_waitcnt lgkmcnt(0)
; __device__ __forceinline__ float silu_f(float g) { return g * __builtin_amdgcn_rcpf(1.f + __expf(-g)); }
; __device__ __forceinline__ unsigned cvtpk(float lo, float hi) { unsigned r; asm volatile("v_cvt_pk_bf16_f32 %0, %1, %2" : "=v"(r) : "v"(lo), "v"(hi)); return r; }
; __device__ __forceinline__ unsigned cvtpk(float lo, float hi) { unsigned r; asm volatile("v_cvt_pk_bf16_f32 %0, %1, %2" : "=v"(r) : "v"(lo), "v"(hi)); return r; }
; __device__ __forceinline__ void attn_body(const bf16_t* Qb, const bf16_t* Kh, const bf16_t* Vh, const bf16_t* Gb, bf16_t* Ob, int seq, char* lds,
;                                           const float* qgain, const float* cosA, const float* sinA, int t0) {
;     ...
;   for (int k = 0; k < 8; ++k) { const int pc = lane & 15, row = (lane >> 4) + 4 * k; const u32x4 ov = *(const u32x4*)(ot + row * 272 + pc * 16); u32x4 w;
; #pragma unroll
;     for (int e = 0; e < 4; ++e) w[e] = cvtpk(bflo(ov[e]) * silu_f(bflo(gq[k][e])), bfhi(ov[e]) * silu_f(bfhi(gq[k][e])));
;     *(u32x4*)(Ow + (long)row * LDO + pc * 8) = w; }
	v_lshlrev_b32_e32 v35, 16, v30
	v_mul_f32_e32 v25, v29, v25
	v_and_b32_e32 v29, 0xffff0000, v30
	v_mul_f32_e32 v20, v34, v20
	v_mul_f32_e32 v25, v25, v35
	v_mul_f32_e32 v20, v20, v29
	v_cvt_pk_bf16_f32 v20, v25, v20
	v_lshlrev_b32_e32 v25, 16, v21
	v_and_b32_e32 v21, 0xffff0000, v21
	v_mul_f32_e32 v29, 0xbfb8aa3b, v25
	v_mul_f32_e32 v30, 0xbfb8aa3b, v21
	v_exp_f32_e32 v29, v29
	v_exp_f32_e32 v30, v30
	v_lshlrev_b32_e32 v34, 16, v31
	v_add_f32_e32 v29, 1.0, v29
	v_add_f32_e32 v30, 1.0, v30
	v_rcp_f32_e32 v29, v29
	v_rcp_f32_e32 v30, v30
	v_mul_f32_e32 v25, v29, v25
	v_and_b32_e32 v29, 0xffff0000, v31
	v_mul_f32_e32 v21, v30, v21
	v_mul_f32_e32 v25, v25, v34
	v_mul_f32_e32 v21, v21, v29
	v_cvt_pk_bf16_f32 v21, v25, v21
	v_lshlrev_b32_e32 v25, 16, v22
	v_and_b32_e32 v22, 0xffff0000, v22
	v_mul_f32_e32 v29, 0xbfb8aa3b, v25
	v_mul_f32_e32 v30, 0xbfb8aa3b, v22
	v_exp_f32_e32 v29, v29
	v_exp_f32_e32 v30, v30
	v_lshlrev_b32_e32 v31, 16, v32
	v_add_f32_e32 v29, 1.0, v29
	v_add_f32_e32 v30, 1.0, v30
	v_rcp_f32_e32 v29, v29
	v_rcp_f32_e32 v30, v30
	v_mul_f32_e32 v25, v29, v25
	v_and_b32_e32 v29, 0xffff0000, v32
	v_mul_f32_e32 v22, v30, v22
	v_mul_f32_e32 v25, v25, v31
	v_mul_f32_e32 v22, v22, v29
	v_cvt_pk_bf16_f32 v22, v25, v22
	v_lshlrev_b32_e32 v25, 16, v23
	v_and_b32_e32 v23, 0xffff0000, v23
	v_mul_f32_e32 v29, 0xbfb8aa3b, v25
	v_mul_f32_e32 v30, 0xbfb8aa3b, v23
	v_exp_f32_e32 v29, v29
	v_exp_f32_e32 v30, v30
	v_lshlrev_b32_e32 v31, 16, v33
	v_add_f32_e32 v29, 1.0, v29
	v_add_f32_e32 v30, 1.0, v30
	v_rcp_f32_e32 v29, v29
	v_rcp_f32_e32 v30, v30
	v_mul_f32_e32 v25, v29, v25
	v_and_b32_e32 v29, 0xffff0000, v33
	v_mul_f32_e32 v23, v30, v23
	v_mul_f32_e32 v25, v25, v31
	v_mul_f32_e32 v23, v23, v29
	v_cvt_pk_bf16_f32 v23, v25, v23
	v_lshl_add_u64 v[30:31], v[26:27], 0, v[176:177]
	s_waitcnt vmcnt(6)
	v_lshlrev_b32_e32 v25, 16, v16
	v_and_b32_e32 v16, 0xffff0000, v16
	global_store_dwordx4 v[30:31], v[20:23], off
	v_mul_f32_e32 v29, 0xbfb8aa3b, v25
	v_mul_f32_e32 v30, 0xbfb8aa3b, v16
	v_exp_f32_e32 v29, v29
	v_exp_f32_e32 v30, v30
	ds_read_b128 v[20:23], v28 offset:3264
	v_or_b32_e32 v176, 0xc000, v24
	v_add_f32_e32 v29, 1.0, v29
	v_add_f32_e32 v30, 1.0, v30
	v_rcp_f32_e32 v29, v29
	v_rcp_f32_e32 v30, v30
	s_waitcnt lgkmcnt(0)
	v_lshlrev_b32_e32 v31, 16, v20
	v_and_b32_e32 v20, 0xffff0000, v20
	v_mul_f32_e32 v25, v29, v25
	v_mul_f32_e32 v16, v30, v16
	v_mul_f32_e32 v25, v25, v31
	v_mul_f32_e32 v16, v16, v20
	v_lshlrev_b32_e32 v20, 16, v17
	v_and_b32_e32 v17, 0xffff0000, v17
	v_cvt_pk_bf16_f32 v16, v25, v16
	v_mul_f32_e32 v25, 0xbfb8aa3b, v20
	v_mul_f32_e32 v29, 0xbfb8aa3b, v17
	v_exp_f32_e32 v25, v25
	v_exp_f32_e32 v29, v29
	v_lshlrev_b32_e32 v30, 16, v21
	v_and_b32_e32 v21, 0xffff0000, v21
	v_add_f32_e32 v25, 1.0, v25
	v_add_f32_e32 v29, 1.0, v29
	v_rcp_f32_e32 v25, v25
	v_rcp_f32_e32 v29, v29
	v_mul_f32_e32 v20, v25, v20
	v_mul_f32_e32 v17, v29, v17
	v_mul_f32_e32 v20, v20, v30
	v_mul_f32_e32 v17, v17, v21
	v_cvt_pk_bf16_f32 v17, v20, v17
	v_lshlrev_b32_e32 v20, 16, v18
	v_and_b32_e32 v18, 0xffff0000, v18
	v_mul_f32_e32 v21, 0xbfb8aa3b, v20
	v_mul_f32_e32 v25, 0xbfb8aa3b, v18
	v_exp_f32_e32 v21, v21
	v_exp_f32_e32 v25, v25
	v_lshlrev_b32_e32 v29, 16, v22
	v_add_f32_e32 v21, 1.0, v21
	v_add_f32_e32 v25, 1.0, v25
	v_rcp_f32_e32 v21, v21
	v_rcp_f32_e32 v25, v25
	v_mul_f32_e32 v20, v21, v20
	v_and_b32_e32 v21, 0xffff0000, v22
	v_mul_f32_e32 v18, v25, v18
	v_mul_f32_e32 v20, v20, v29
	v_mul_f32_e32 v18, v18, v21
	v_cvt_pk_bf16_f32 v18, v20, v18
	v_lshlrev_b32_e32 v20, 16, v19
	v_and_b32_e32 v19, 0xffff0000, v19
	v_mul_f32_e32 v21, 0xbfb8aa3b, v20
	v_mul_f32_e32 v22, 0xbfb8aa3b, v19
	v_exp_f32_e32 v21, v21
	v_exp_f32_e32 v22, v22
	v_lshlrev_b32_e32 v25, 16, v23
	v_add_f32_e32 v21, 1.0, v21
	v_add_f32_e32 v22, 1.0, v22
	v_rcp_f32_e32 v21, v21
	v_rcp_f32_e32 v22, v22
	v_mul_f32_e32 v20, v21, v20
	v_and_b32_e32 v21, 0xffff0000, v23
	v_mul_f32_e32 v19, v22, v19
	v_mul_f32_e32 v20, v20, v25
	v_mul_f32_e32 v19, v19, v21
	v_cvt_pk_bf16_f32 v19, v20, v19
	v_lshl_add_u64 v[20:21], v[26:27], 0, v[176:177]
	global_store_dwordx4 v[20:21], v[16:19], off
	s_waitcnt vmcnt(7)
	v_lshlrev_b32_e32 v20, 16, v12
	v_and_b32_e32 v12, 0xffff0000, v12
	v_mul_f32_e32 v21, 0xbfb8aa3b, v20
	v_mul_f32_e32 v22, 0xbfb8aa3b, v12
	v_exp_f32_e32 v21, v21
	v_exp_f32_e32 v22, v22
	ds_read_b128 v[16:19], v28 offset:4352
	v_or_b32_e32 v176, 0x10000, v24
	v_add_f32_e32 v21, 1.0, v21
	v_add_f32_e32 v22, 1.0, v22
	v_rcp_f32_e32 v21, v21
	v_rcp_f32_e32 v22, v22
	s_waitcnt lgkmcnt(0)
	v_lshlrev_b32_e32 v23, 16, v16
	v_and_b32_e32 v16, 0xffff0000, v16
	v_mul_f32_e32 v20, v21, v20
	v_mul_f32_e32 v12, v22, v12
	v_mul_f32_e32 v20, v20, v23
	v_mul_f32_e32 v12, v12, v16
	v_lshlrev_b32_e32 v16, 16, v13
	v_and_b32_e32 v13, 0xffff0000, v13
	v_cvt_pk_bf16_f32 v12, v20, v12
	v_mul_f32_e32 v20, 0xbfb8aa3b, v16
	v_mul_f32_e32 v21, 0xbfb8aa3b, v13
	v_exp_f32_e32 v20, v20
	v_exp_f32_e32 v21, v21
	v_lshlrev_b32_e32 v22, 16, v17
	v_and_b32_e32 v17, 0xffff0000, v17
	v_add_f32_e32 v20, 1.0, v20
	v_add_f32_e32 v21, 1.0, v21
	v_rcp_f32_e32 v20, v20
	v_rcp_f32_e32 v21, v21
	v_mul_f32_e32 v16, v20, v16
	v_mul_f32_e32 v13, v21, v13
	v_mul_f32_e32 v16, v16, v22
	v_mul_f32_e32 v13, v13, v17
	v_cvt_pk_bf16_f32 v13, v16, v13
	v_lshlrev_b32_e32 v16, 16, v14
	v_and_b32_e32 v14, 0xffff0000, v14
	v_mul_f32_e32 v17, 0xbfb8aa3b, v16
	v_mul_f32_e32 v20, 0xbfb8aa3b, v14
	v_exp_f32_e32 v17, v17
	v_exp_f32_e32 v20, v20
	v_lshlrev_b32_e32 v21, 16, v18
	v_add_f32_e32 v17, 1.0, v17
	v_add_f32_e32 v20, 1.0, v20
	v_rcp_f32_e32 v17, v17
	v_rcp_f32_e32 v20, v20
	v_mul_f32_e32 v16, v17, v16
	v_and_b32_e32 v17, 0xffff0000, v18
	v_mul_f32_e32 v14, v20, v14
	v_mul_f32_e32 v16, v16, v21
	v_mul_f32_e32 v14, v14, v17
	v_cvt_pk_bf16_f32 v14, v16, v14
	v_lshlrev_b32_e32 v16, 16, v15
	v_and_b32_e32 v15, 0xffff0000, v15
	v_mul_f32_e32 v17, 0xbfb8aa3b, v16
	v_mul_f32_e32 v18, 0xbfb8aa3b, v15
	v_exp_f32_e32 v17, v17
	v_exp_f32_e32 v18, v18
	v_lshlrev_b32_e32 v20, 16, v19
	v_add_f32_e32 v17, 1.0, v17
	v_add_f32_e32 v18, 1.0, v18
	v_rcp_f32_e32 v17, v17
	v_rcp_f32_e32 v18, v18
	v_mul_f32_e32 v16, v17, v16
	v_and_b32_e32 v17, 0xffff0000, v19
	v_mul_f32_e32 v15, v18, v15
	v_mul_f32_e32 v16, v16, v20
	v_mul_f32_e32 v15, v15, v17
	v_cvt_pk_bf16_f32 v15, v16, v15
	v_lshl_add_u64 v[16:17], v[26:27], 0, v[176:177]
	global_store_dwordx4 v[16:17], v[12:15], off
	s_waitcnt vmcnt(7)
; __device__ __forceinline__ float silu_f(float g) { return g * __builtin_amdgcn_rcpf(1.f + __expf(-g)); }
; __device__ __forceinline__ unsigned cvtpk(float lo, float hi) { unsigned r; asm volatile("v_cvt_pk_bf16_f32 %0, %1, %2" : "=v"(r) : "v"(lo), "v"(hi)); return r; }
; __device__ __forceinline__ unsigned cvtpk(float lo, float hi) { unsigned r; asm volatile("v_cvt_pk_bf16_f32 %0, %1, %2" : "=v"(r) : "v"(lo), "v"(hi)); return r; }
; __device__ __forceinline__ void attn_body(const bf16_t* Qb, const bf16_t* Kh, const bf16_t* Vh, const bf16_t* Gb, bf16_t* Ob, int seq, char* lds,
;                                           const float* qgain, const float* cosA, const float* sinA, int t0) {
;     ...
;   for (int k = 0; k < 8; ++k) { const int pc = lane & 15, row = (lane >> 4) + 4 * k; const u32x4 ov = *(const u32x4*)(ot + row * 272 + pc * 16); u32x4 w;
; #pragma unroll
;     for (int e = 0; e < 4; ++e) w[e] = cvtpk(bflo(ov[e]) * silu_f(bflo(gq[k][e])), bfhi(ov[e]) * silu_f(bfhi(gq[k][e])));
;     *(u32x4*)(Ow + (long)row * LDO + pc * 8) = w; }
; __global__ void __launch_bounds__(512, 2) mega_fwd(Params p) {
;     ...
;                 __syncthreads();
	v_lshlrev_b32_e32 v16, 16, v8
	v_and_b32_e32 v8, 0xffff0000, v8
	v_mul_f32_e32 v17, 0xbfb8aa3b, v16
	v_mul_f32_e32 v18, 0xbfb8aa3b, v8
	v_exp_f32_e32 v17, v17
	v_exp_f32_e32 v18, v18
	ds_read_b128 v[12:15], v28 offset:5440
	v_or_b32_e32 v176, 0x14000, v24
	v_add_f32_e32 v17, 1.0, v17
	v_add_f32_e32 v18, 1.0, v18
	v_rcp_f32_e32 v17, v17
	v_rcp_f32_e32 v18, v18
	s_waitcnt lgkmcnt(0)
	v_lshlrev_b32_e32 v19, 16, v12
	v_and_b32_e32 v12, 0xffff0000, v12
	v_mul_f32_e32 v16, v17, v16
	v_mul_f32_e32 v8, v18, v8
	v_mul_f32_e32 v16, v16, v19
	v_mul_f32_e32 v8, v8, v12
	v_lshlrev_b32_e32 v12, 16, v9
	v_and_b32_e32 v9, 0xffff0000, v9
	v_cvt_pk_bf16_f32 v8, v16, v8
	v_mul_f32_e32 v16, 0xbfb8aa3b, v12
	v_mul_f32_e32 v17, 0xbfb8aa3b, v9
	v_exp_f32_e32 v16, v16
	v_exp_f32_e32 v17, v17
	v_lshlrev_b32_e32 v18, 16, v13
	v_and_b32_e32 v13, 0xffff0000, v13
	v_add_f32_e32 v16, 1.0, v16
	v_add_f32_e32 v17, 1.0, v17
	v_rcp_f32_e32 v16, v16
	v_rcp_f32_e32 v17, v17
	v_mul_f32_e32 v12, v16, v12
	v_mul_f32_e32 v9, v17, v9
	v_mul_f32_e32 v12, v12, v18
	v_mul_f32_e32 v9, v9, v13
	v_cvt_pk_bf16_f32 v9, v12, v9
	v_lshlrev_b32_e32 v12, 16, v10
	v_and_b32_e32 v10, 0xffff0000, v10
	v_mul_f32_e32 v13, 0xbfb8aa3b, v12
	v_mul_f32_e32 v16, 0xbfb8aa3b, v10
	v_exp_f32_e32 v13, v13
	v_exp_f32_e32 v16, v16
	v_lshlrev_b32_e32 v17, 16, v14
	v_add_f32_e32 v13, 1.0, v13
	v_add_f32_e32 v16, 1.0, v16
	v_rcp_f32_e32 v13, v13
	v_rcp_f32_e32 v16, v16
	v_mul_f32_e32 v12, v13, v12
	v_and_b32_e32 v13, 0xffff0000, v14
	v_mul_f32_e32 v10, v16, v10
	v_mul_f32_e32 v12, v12, v17
	v_mul_f32_e32 v10, v10, v13
	v_cvt_pk_bf16_f32 v10, v12, v10
	v_lshlrev_b32_e32 v12, 16, v11
	v_and_b32_e32 v11, 0xffff0000, v11
	v_mul_f32_e32 v13, 0xbfb8aa3b, v12
	v_mul_f32_e32 v14, 0xbfb8aa3b, v11
	v_exp_f32_e32 v13, v13
	v_exp_f32_e32 v14, v14
	v_lshlrev_b32_e32 v16, 16, v15
	v_add_f32_e32 v13, 1.0, v13
	v_add_f32_e32 v14, 1.0, v14
	v_rcp_f32_e32 v13, v13
	v_rcp_f32_e32 v14, v14
	v_mul_f32_e32 v12, v13, v12
	v_and_b32_e32 v13, 0xffff0000, v15
	v_mul_f32_e32 v11, v14, v11
	v_mul_f32_e32 v12, v12, v16
	v_mul_f32_e32 v11, v11, v13
	v_cvt_pk_bf16_f32 v11, v12, v11
	v_lshl_add_u64 v[12:13], v[26:27], 0, v[176:177]
	global_store_dwordx4 v[12:13], v[8:11], off
	s_waitcnt vmcnt(7)
	v_lshlrev_b32_e32 v12, 16, v4
	v_and_b32_e32 v4, 0xffff0000, v4
	v_mul_f32_e32 v13, 0xbfb8aa3b, v12
	v_mul_f32_e32 v14, 0xbfb8aa3b, v4
	v_exp_f32_e32 v13, v13
	v_exp_f32_e32 v14, v14
	ds_read_b128 v[8:11], v28 offset:6528
	v_or_b32_e32 v176, 0x18000, v24
	v_add_f32_e32 v13, 1.0, v13
	v_add_f32_e32 v14, 1.0, v14
	v_rcp_f32_e32 v13, v13
	v_rcp_f32_e32 v14, v14
	s_waitcnt lgkmcnt(0)
	v_lshlrev_b32_e32 v15, 16, v8
	v_and_b32_e32 v8, 0xffff0000, v8
	v_mul_f32_e32 v12, v13, v12
	v_mul_f32_e32 v4, v14, v4
	v_mul_f32_e32 v12, v12, v15
	v_mul_f32_e32 v4, v4, v8
	v_lshlrev_b32_e32 v8, 16, v5
	v_and_b32_e32 v5, 0xffff0000, v5
	v_cvt_pk_bf16_f32 v4, v12, v4
	v_mul_f32_e32 v12, 0xbfb8aa3b, v8
	v_mul_f32_e32 v13, 0xbfb8aa3b, v5
	v_exp_f32_e32 v12, v12
	v_exp_f32_e32 v13, v13
	v_lshlrev_b32_e32 v14, 16, v9
	v_and_b32_e32 v9, 0xffff0000, v9
	v_add_f32_e32 v12, 1.0, v12
	v_add_f32_e32 v13, 1.0, v13
	v_rcp_f32_e32 v12, v12
	v_rcp_f32_e32 v13, v13
	v_mul_f32_e32 v8, v12, v8
	v_mul_f32_e32 v5, v13, v5
	v_mul_f32_e32 v8, v8, v14
	v_mul_f32_e32 v5, v5, v9
	v_cvt_pk_bf16_f32 v5, v8, v5
	v_lshlrev_b32_e32 v8, 16, v6
	v_and_b32_e32 v6, 0xffff0000, v6
	v_mul_f32_e32 v9, 0xbfb8aa3b, v8
	v_mul_f32_e32 v12, 0xbfb8aa3b, v6
	v_exp_f32_e32 v9, v9
	v_exp_f32_e32 v12, v12
	v_lshlrev_b32_e32 v13, 16, v10
	v_add_f32_e32 v9, 1.0, v9
	v_add_f32_e32 v12, 1.0, v12
	v_rcp_f32_e32 v9, v9
	v_rcp_f32_e32 v12, v12
	v_mul_f32_e32 v8, v9, v8
	v_and_b32_e32 v9, 0xffff0000, v10
	v_mul_f32_e32 v6, v12, v6
	v_mul_f32_e32 v8, v8, v13
	v_mul_f32_e32 v6, v6, v9
	v_cvt_pk_bf16_f32 v6, v8, v6
	v_lshlrev_b32_e32 v8, 16, v7
	v_and_b32_e32 v7, 0xffff0000, v7
	v_mul_f32_e32 v9, 0xbfb8aa3b, v8
	v_mul_f32_e32 v10, 0xbfb8aa3b, v7
	v_exp_f32_e32 v9, v9
	v_exp_f32_e32 v10, v10
	v_lshlrev_b32_e32 v12, 16, v11
	v_add_f32_e32 v9, 1.0, v9
	v_add_f32_e32 v10, 1.0, v10
	v_rcp_f32_e32 v9, v9
	v_rcp_f32_e32 v10, v10
	v_mul_f32_e32 v8, v9, v8
	v_and_b32_e32 v9, 0xffff0000, v11
	v_mul_f32_e32 v7, v10, v7
	v_mul_f32_e32 v8, v8, v12
	v_mul_f32_e32 v7, v7, v9
	v_cvt_pk_bf16_f32 v7, v8, v7
	v_lshl_add_u64 v[8:9], v[26:27], 0, v[176:177]
	global_store_dwordx4 v[8:9], v[4:7], off
	s_waitcnt vmcnt(7)
	v_lshlrev_b32_e32 v8, 16, v0
	v_and_b32_e32 v0, 0xffff0000, v0
	v_mul_f32_e32 v9, 0xbfb8aa3b, v8
	v_mul_f32_e32 v10, 0xbfb8aa3b, v0
	v_exp_f32_e32 v9, v9
	v_exp_f32_e32 v10, v10
	ds_read_b128 v[4:7], v28 offset:7616
	v_or_b32_e32 v176, 0x1c000, v24
	v_add_f32_e32 v9, 1.0, v9
	v_add_f32_e32 v10, 1.0, v10
	v_rcp_f32_e32 v9, v9
	v_rcp_f32_e32 v10, v10
	s_waitcnt lgkmcnt(0)
	v_lshlrev_b32_e32 v11, 16, v4
	v_and_b32_e32 v4, 0xffff0000, v4
	v_mul_f32_e32 v8, v9, v8
	v_mul_f32_e32 v0, v10, v0
	v_mul_f32_e32 v8, v8, v11
	v_mul_f32_e32 v0, v0, v4
	v_lshlrev_b32_e32 v4, 16, v1
	v_and_b32_e32 v1, 0xffff0000, v1
	v_cvt_pk_bf16_f32 v0, v8, v0
	v_mul_f32_e32 v8, 0xbfb8aa3b, v4
	v_mul_f32_e32 v9, 0xbfb8aa3b, v1
	v_exp_f32_e32 v8, v8
	v_exp_f32_e32 v9, v9
	v_lshlrev_b32_e32 v10, 16, v5
	v_and_b32_e32 v5, 0xffff0000, v5
	v_add_f32_e32 v8, 1.0, v8
	v_add_f32_e32 v9, 1.0, v9
	v_rcp_f32_e32 v8, v8
	v_rcp_f32_e32 v9, v9
	v_mul_f32_e32 v4, v8, v4
	v_mul_f32_e32 v1, v9, v1
	v_mul_f32_e32 v4, v4, v10
	v_mul_f32_e32 v1, v1, v5
	v_cvt_pk_bf16_f32 v1, v4, v1
	v_lshlrev_b32_e32 v4, 16, v2
	v_and_b32_e32 v2, 0xffff0000, v2
	v_mul_f32_e32 v5, 0xbfb8aa3b, v4
	v_mul_f32_e32 v8, 0xbfb8aa3b, v2
	v_exp_f32_e32 v5, v5
	v_exp_f32_e32 v8, v8
	v_lshlrev_b32_e32 v9, 16, v6
	v_add_f32_e32 v5, 1.0, v5
	v_add_f32_e32 v8, 1.0, v8
	v_rcp_f32_e32 v5, v5
	v_rcp_f32_e32 v8, v8
	v_mul_f32_e32 v4, v5, v4
	v_and_b32_e32 v5, 0xffff0000, v6
	v_mul_f32_e32 v2, v8, v2
	v_mul_f32_e32 v4, v4, v9
	v_mul_f32_e32 v2, v2, v5
	v_cvt_pk_bf16_f32 v2, v4, v2
	v_lshlrev_b32_e32 v4, 16, v3
	v_and_b32_e32 v3, 0xffff0000, v3
	v_mul_f32_e32 v5, 0xbfb8aa3b, v4
	v_mul_f32_e32 v6, 0xbfb8aa3b, v3
	v_exp_f32_e32 v5, v5
	v_exp_f32_e32 v6, v6
	v_lshlrev_b32_e32 v8, 16, v7
	v_add_f32_e32 v5, 1.0, v5
	v_add_f32_e32 v6, 1.0, v6
	v_rcp_f32_e32 v5, v5
	v_rcp_f32_e32 v6, v6
	v_mul_f32_e32 v4, v5, v4
	v_and_b32_e32 v5, 0xffff0000, v7
	v_mul_f32_e32 v3, v6, v3
	v_mul_f32_e32 v4, v4, v8
	v_mul_f32_e32 v3, v3, v5
	v_cvt_pk_bf16_f32 v3, v4, v3
	v_lshl_add_u64 v[4:5], v[26:27], 0, v[176:177]
	global_store_dwordx4 v[4:5], v[0:3], off
	s_barrier
	s_cbranch_scc1 .LBB0_277
